# grid barrier: non-leader workgroups poll the cross-XCD arrival counter against (generation+1)*populated XCDs, one atomic hop less
# speedup vs baseline: 1.0001x; 1.0001x over previous
; __device__ __forceinline__ unsigned xb_ld(unsigned* p)              { return __hip_atomic_load(p, __ATOMIC_RELAXED, __HIP_MEMORY_SCOPE_AGENT); }
; __device__ __forceinline__ unsigned xb_add(unsigned* p, unsigned v) { return __hip_atomic_fetch_add(p, v, __ATOMIC_RELAXED, __HIP_MEMORY_SCOPE_AGENT); }
; #define XB_SPIN(cond, bar) do { unsigned _sp = 0; while (cond) { __builtin_amdgcn_s_sleep(1); \
;     if ((++_sp & 255u) == 0u) { if (xb_ld(&(bar)[XB_TMO])) break; if (_sp > XB_SPIN_CAP) { atomicAdd(&(bar)[XB_TMO], 1u); break; } } } } while (0)
; __device__ __forceinline__ void xcd_barrier(const XcdBarrier& b) {
;     ...
;         unsigned nloc = b.st[0], nx = b.st[1];
;         if (nloc == 0u) { xcd_barrier_complete(bar, bx_, nloc, nx); b.st[0] = nloc; b.st[1] = nx; }
;         const unsigned old = xb_add(&bar[XB_XSUB(bx_)], 1u);
;         const unsigned gen = old / nloc;
;         if (old + 1u == (gen + 1u) * nloc) {
;             __builtin_amdgcn_fence(__ATOMIC_RELEASE, "agent");
;             asm volatile("s_waitcnt vmcnt(0)" ::: "memory");
;             const unsigned og = xb_add(&bar[XB_TOP], 1u);
;             const unsigned tg = og / nx;
;             if (og + 1u == (tg + 1u) * nx) xb_add(&bar[XB_TOPGEN], 1u);
;             else XB_SPIN(xb_ld(&bar[XB_TOPGEN]) == tg, bar);
;             __builtin_amdgcn_fence(__ATOMIC_ACQUIRE, "agent");
;             xb_add(&bar[XB_XGEN(bx_)], 1u);
;             asm volatile("s_waitcnt vmcnt(0)" ::: "memory");
;         } else {
;             XB_SPIN(xb_ld(&bar[XB_XGEN(bx_)]) == gen, bar);
;             __builtin_amdgcn_fence(__ATOMIC_ACQUIRE, "agent");
;             asm volatile("s_waitcnt vmcnt(0)" ::: "memory");
.LBB0_250:
	s_or_b64 exec, exec, s[6:7]
	v_cvt_f32_u32_e32 v5, v3
	s_waitcnt vmcnt(0)
	v_readfirstlane_b32 s4, v4
	v_sub_u32_e32 v4, 0, v3
	v_rcp_iflag_f32_e32 v5, v5
	v_add_u32_e32 v6, s4, v2
	v_mul_f32_e32 v5, 0x4f7ffffe, v5
	v_cvt_u32_f32_e32 v5, v5
	v_mul_lo_u32 v2, v4, v5
	v_mul_hi_u32 v2, v5, v2
	v_add_u32_e32 v2, v5, v2
	v_mul_hi_u32 v2, v6, v2
	v_mul_lo_u32 v4, v2, v3
	v_sub_u32_e32 v4, v6, v4
	v_add_u32_e32 v5, 1, v2
	v_cmp_ge_u32_e32 vcc, v4, v3
	s_nop 1
	v_cndmask_b32_e32 v2, v2, v5, vcc
	v_sub_u32_e32 v5, v4, v3
	v_cndmask_b32_e32 v4, v4, v5, vcc
	v_add_u32_e32 v5, 1, v2
	v_cmp_ge_u32_e32 vcc, v4, v3
	v_add_u32_e32 v4, 1, v6
	s_nop 0
	v_cndmask_b32_e32 v2, v2, v5, vcc
	v_mul_lo_u32 v5, v3, v2
	v_add_u32_e32 v3, v5, v3
	v_cmp_ne_u32_e32 vcc, v4, v3
	s_and_saveexec_b64 s[4:5], vcc
	s_xor_b64 s[4:5], exec, s[4:5]
	s_cbranch_execz .LBB0_264
	s_waitcnt lgkmcnt(0)
	v_readlane_b32 s10, v252, 16
	v_readlane_b32 s11, v252, 17
	v_mov_b32_e32 v8, 0x20164
	ds_read_b32 v8, v8
	v_mov_b32_e32 v1, 0
	v_add_u32_e32 v10, 1, v2
	s_add_u32 s10, s10, 0x7400
	s_addc_u32 s11, s11, 0
	global_load_dword v1, v1, s[10:11] sc1
	s_waitcnt lgkmcnt(0)
	v_mul_lo_u32 v8, v8, v10
	s_waitcnt vmcnt(0)
	v_cmp_lt_u32_e32 vcc, v1, v8
	s_and_saveexec_b64 s[6:7], vcc
	s_cbranch_execz .LBB0_263
	v_readlane_b32 s12, v252, 2
	v_readlane_b32 s26, v252, 16
	v_readlane_b32 s13, v252, 3
	v_readlane_b32 s22, v252, 12
	v_readlane_b32 s27, v252, 17
	s_add_u32 s8, s26, 0x4200
	v_readlane_b32 s14, v252, 4
	v_readlane_b32 s15, v252, 5
	s_addc_u32 s9, s27, 0
	s_mov_b32 s22, 1
	s_mov_b64 s[12:13], 0
	v_mov_b32_e32 v1, 0
	v_readlane_b32 s16, v252, 6
	v_readlane_b32 s17, v252, 7
	v_readlane_b32 s18, v252, 8
	v_readlane_b32 s19, v252, 9
	v_readlane_b32 s20, v252, 10
	v_readlane_b32 s21, v252, 11
	v_readlane_b32 s23, v252, 13
	v_readlane_b32 s24, v252, 14
	v_readlane_b32 s25, v252, 15
	s_branch .LBB0_254

; __device__ __forceinline__ unsigned xb_ld(unsigned* p)              { return __hip_atomic_load(p, __ATOMIC_RELAXED, __HIP_MEMORY_SCOPE_AGENT); }
; #define XB_SPIN(cond, bar) do { unsigned _sp = 0; while (cond) { __builtin_amdgcn_s_sleep(1); \
;     if ((++_sp & 255u) == 0u) { if (xb_ld(&(bar)[XB_TMO])) break; if (_sp > XB_SPIN_CAP) { atomicAdd(&(bar)[XB_TMO], 1u); break; } } } } while (0)
; __device__ __forceinline__ void xcd_barrier(const XcdBarrier& b) {
;     ...
;             XB_SPIN(xb_ld(&bar[XB_XGEN(bx_)]) == gen, bar);
.LBB0_258:
	global_load_dword v3, v1, s[10:11] sc1
	s_add_i32 s22, s22, 1
	s_mov_b64 s[18:19], -1
	s_waitcnt vmcnt(0)
	v_cmp_ge_u32_e32 vcc, v3, v8
	s_orn2_b64 s[16:17], vcc, exec
	s_branch .LBB0_253

; __device__ __forceinline__ unsigned xb_ld(unsigned* p)              { return __hip_atomic_load(p, __ATOMIC_RELAXED, __HIP_MEMORY_SCOPE_AGENT); }
; __device__ __forceinline__ unsigned xb_add(unsigned* p, unsigned v) { return __hip_atomic_fetch_add(p, v, __ATOMIC_RELAXED, __HIP_MEMORY_SCOPE_AGENT); }
; #define XB_SPIN(cond, bar) do { unsigned _sp = 0; while (cond) { __builtin_amdgcn_s_sleep(1); \
;     if ((++_sp & 255u) == 0u) { if (xb_ld(&(bar)[XB_TMO])) break; if (_sp > XB_SPIN_CAP) { atomicAdd(&(bar)[XB_TMO], 1u); break; } } } } while (0)
; __device__ __forceinline__ void xcd_barrier(const XcdBarrier& b) {
;     ...
;         unsigned nloc = b.st[0], nx = b.st[1];
;         if (nloc == 0u) { xcd_barrier_complete(bar, bx_, nloc, nx); b.st[0] = nloc; b.st[1] = nx; }
;         const unsigned old = xb_add(&bar[XB_XSUB(bx_)], 1u);
;         const unsigned gen = old / nloc;
;         if (old + 1u == (gen + 1u) * nloc) {
;             __builtin_amdgcn_fence(__ATOMIC_RELEASE, "agent");
;             asm volatile("s_waitcnt vmcnt(0)" ::: "memory");
;             const unsigned og = xb_add(&bar[XB_TOP], 1u);
;             const unsigned tg = og / nx;
;             if (og + 1u == (tg + 1u) * nx) xb_add(&bar[XB_TOPGEN], 1u);
;             else XB_SPIN(xb_ld(&bar[XB_TOPGEN]) == tg, bar);
;             __builtin_amdgcn_fence(__ATOMIC_ACQUIRE, "agent");
;             xb_add(&bar[XB_XGEN(bx_)], 1u);
;             asm volatile("s_waitcnt vmcnt(0)" ::: "memory");
;         } else {
;             XB_SPIN(xb_ld(&bar[XB_XGEN(bx_)]) == gen, bar);
;             __builtin_amdgcn_fence(__ATOMIC_ACQUIRE, "agent");
;             asm volatile("s_waitcnt vmcnt(0)" ::: "memory");
.LBB0_510:
	s_or_b64 exec, exec, s[6:7]
	v_cvt_f32_u32_e32 v7, v5
	s_waitcnt vmcnt(0)
	v_readfirstlane_b32 s4, v6
	v_sub_u32_e32 v6, 0, v5
	v_rcp_iflag_f32_e32 v7, v7
	v_add_u32_e32 v8, s4, v2
	v_mul_f32_e32 v7, 0x4f7ffffe, v7
	v_cvt_u32_f32_e32 v7, v7
	v_mul_lo_u32 v2, v6, v7
	v_mul_hi_u32 v2, v7, v2
	v_add_u32_e32 v2, v7, v2
	v_mul_hi_u32 v2, v8, v2
	v_mul_lo_u32 v6, v2, v5
	v_sub_u32_e32 v6, v8, v6
	v_add_u32_e32 v7, 1, v2
	v_cmp_ge_u32_e32 vcc, v6, v5
	s_nop 1
	v_cndmask_b32_e32 v2, v2, v7, vcc
	v_sub_u32_e32 v7, v6, v5
	v_cndmask_b32_e32 v6, v6, v7, vcc
	v_add_u32_e32 v7, 1, v2
	v_cmp_ge_u32_e32 vcc, v6, v5
	v_add_u32_e32 v6, 1, v8
	s_nop 0
	v_cndmask_b32_e32 v2, v2, v7, vcc
	v_mul_lo_u32 v7, v5, v2
	v_add_u32_e32 v5, v7, v5
	v_cmp_ne_u32_e32 vcc, v6, v5
	s_and_saveexec_b64 s[4:5], vcc
	s_xor_b64 s[4:5], exec, s[4:5]
	s_cbranch_execz .LBB0_524
	s_waitcnt lgkmcnt(0)
	v_readlane_b32 s8, v252, 16
	v_readlane_b32 s9, v252, 17
	v_mov_b32_e32 v8, 0x20164
	ds_read_b32 v8, v8
	v_mov_b32_e32 v4, 0
	v_add_u32_e32 v10, 1, v2
	s_add_u32 s8, s8, 0x7400
	s_addc_u32 s9, s9, 0
	global_load_dword v4, v4, s[8:9] sc1
	s_waitcnt lgkmcnt(0)
	v_mul_lo_u32 v8, v8, v10
	s_waitcnt vmcnt(0)
	v_cmp_lt_u32_e32 vcc, v4, v8
	s_and_saveexec_b64 s[6:7], vcc
	s_cbranch_execz .LBB0_523
	s_mov_b32 s20, 1
	s_mov_b64 s[10:11], 0
	s_branch .LBB0_514

; __device__ __forceinline__ unsigned xb_ld(unsigned* p)              { return __hip_atomic_load(p, __ATOMIC_RELAXED, __HIP_MEMORY_SCOPE_AGENT); }
; #define XB_SPIN(cond, bar) do { unsigned _sp = 0; while (cond) { __builtin_amdgcn_s_sleep(1); \
;     if ((++_sp & 255u) == 0u) { if (xb_ld(&(bar)[XB_TMO])) break; if (_sp > XB_SPIN_CAP) { atomicAdd(&(bar)[XB_TMO], 1u); break; } } } } while (0)
; __device__ __forceinline__ void xcd_barrier(const XcdBarrier& b) {
;     ...
;             XB_SPIN(xb_ld(&bar[XB_XGEN(bx_)]) == gen, bar);
.LBB0_518:
	global_load_dword v4, v3, s[8:9] sc1
	s_add_i32 s20, s20, 1
	s_mov_b64 s[16:17], -1
	s_waitcnt vmcnt(0)
	v_cmp_ge_u32_e32 vcc, v4, v8
	s_orn2_b64 s[14:15], vcc, exec
	s_branch .LBB0_513
